# strategy 2 epilogue de-serialisation: gemm_f32 store part with 8 LDS reads in flight and incremental store addresses
# speedup vs baseline: 1.0052x; 1.0015x over previous
; template <int MI, int NJ> ...
;     ...
;   for (int kt = 0; kt < nk; ++kt) {
;     const int buf = kt & 1;
;     {
;       G8STORE(buf ^ 1);
;       const u16* ga_ = (kt + 2 < nk) ? Ag + (kt + 2) * 64 : Ag + nAoff;
;       const u16* gb_ = (kt + 2 < nk) ? Bg + (kt + 2) * 64 : Bg + nBoff;
;       G8LOADP(ga_, gb_);
;     }
;     __builtin_amdgcn_sched_barrier(0);
;     __builtin_amdgcn_s_setprio(1);
;     const u16* a = ra_ + buf * AROWS * 64;
;     const u16* b = rb_ + buf * BROWS * 64;
; #pragma unroll
;     for (int ks = 0; ks < 2; ++ks) {
;       const u16* a_ = ks ? a + dsw : a;
;       const u16* b_ = ks ? b + dsw : b;
;       bf16x8 bfr[NJ];
; #pragma unroll
;       for (int j = 0; j < NJ; ++j) bfr[j] = *(const bf16x8*)(b_ + j * 16 * 64);
; #pragma unroll
;       for (int ih = 0; ih < MI / 4; ++ih) {
;         bf16x8 af[4];
; #pragma unroll
;         for (int i = 0; i < 4; ++i) af[i] = *(const bf16x8*)(a_ + (ih * 4 + i) * 16 * 64);
; #pragma unroll
;         for (int i = 0; i < 4; ++i)
; #pragma unroll
;           for (int j = 0; j < NJ; ++j) acc[ih * 4 + i][j] = mfma16(af[i], bfr[j], acc[ih * 4 + i][j]);
;       }
;     }
;     __builtin_amdgcn_s_setprio(0);
;     __builtin_amdgcn_sched_barrier(0);
;     __syncthreads();
.LBB0_481:
	s_setprio 1
	s_waitcnt lgkmcnt(6)
	v_mfma_f32_16x16x32_bf16 v[158:161], v[166:169], v[162:165], v[158:161]
	s_waitcnt lgkmcnt(5)
	v_mfma_f32_16x16x32_bf16 v[154:157], v[170:173], v[162:165], v[154:157]
	s_waitcnt lgkmcnt(4)
	v_mfma_f32_16x16x32_bf16 v[150:153], v[192:195], v[162:165], v[150:153]
	s_waitcnt lgkmcnt(3)
	v_mfma_f32_16x16x32_bf16 v[146:149], v[196:199], v[162:165], v[146:149]
	ds_read_b128 v[162:165], v0 offset:8192
	s_waitcnt lgkmcnt(3)
	v_mfma_f32_16x16x32_bf16 v[142:145], v[166:169], v[204:207], v[142:145]
	v_mfma_f32_16x16x32_bf16 v[138:141], v[170:173], v[204:207], v[138:141]
	v_mfma_f32_16x16x32_bf16 v[134:137], v[192:195], v[204:207], v[134:137]
	v_mfma_f32_16x16x32_bf16 v[130:133], v[196:199], v[204:207], v[130:133]
	ds_read_b128 v[204:207], v0 offset:10240
	s_waitcnt lgkmcnt(3)
	v_mfma_f32_16x16x32_bf16 v[126:129], v[166:169], v[208:211], v[126:129]
	v_mfma_f32_16x16x32_bf16 v[122:125], v[170:173], v[208:211], v[122:125]
	v_mfma_f32_16x16x32_bf16 v[118:121], v[192:195], v[208:211], v[118:121]
	v_mfma_f32_16x16x32_bf16 v[114:117], v[196:199], v[208:211], v[114:117]
	ds_read_b128 v[208:211], v0 offset:12288
	ds_read_b128 v[212:215], v191
	ds_read_b128 v[216:219], v191 offset:2048
	s_waitcnt lgkmcnt(5)
	v_mfma_f32_16x16x32_bf16 v[110:113], v[166:169], v[238:241], v[110:113]
	v_mfma_f32_16x16x32_bf16 v[106:109], v[170:173], v[238:241], v[106:109]
	v_mfma_f32_16x16x32_bf16 v[102:105], v[192:195], v[238:241], v[102:105]
	v_mfma_f32_16x16x32_bf16 v[98:101], v[196:199], v[238:241], v[98:101]
	ds_read_b128 v[238:241], v0 offset:14336
	ds_read_b128 v[220:223], v191 offset:4096
	ds_read_b128 v[224:227], v191 offset:6144
	s_waitcnt lgkmcnt(7)
	v_mfma_f32_16x16x32_bf16 v[94:97], v[166:169], v[162:165], v[94:97]
	v_mfma_f32_16x16x32_bf16 v[90:93], v[170:173], v[162:165], v[90:93]
	v_mfma_f32_16x16x32_bf16 v[86:89], v[192:195], v[162:165], v[86:89]
	v_mfma_f32_16x16x32_bf16 v[82:85], v[196:199], v[162:165], v[82:85]
	v_add_u32_e32 v0, v0, v190
	ds_read_b128 v[162:165], v0
	s_waitcnt vmcnt(7)
	ds_write_b128 v228, v[10:13]
	global_load_dwordx4 v[10:13], v234, s[50:51]
	s_waitcnt lgkmcnt(8)
	v_mfma_f32_16x16x32_bf16 v[78:81], v[166:169], v[204:207], v[78:81]
	v_mfma_f32_16x16x32_bf16 v[70:73], v[170:173], v[204:207], v[70:73]
	v_mfma_f32_16x16x32_bf16 v[66:69], v[192:195], v[204:207], v[66:69]
	v_mfma_f32_16x16x32_bf16 v[58:61], v[196:199], v[204:207], v[58:61]
	ds_read_b128 v[204:207], v0 offset:2048
	s_waitcnt vmcnt(7)
	ds_write_b128 v228, v[2:5] offset:8192
	global_load_dwordx4 v[2:5], v235, s[50:51]
	s_waitcnt lgkmcnt(9)
	v_mfma_f32_16x16x32_bf16 v[54:57], v[166:169], v[208:211], v[54:57]
	v_mfma_f32_16x16x32_bf16 v[50:53], v[170:173], v[208:211], v[50:53]
	v_mfma_f32_16x16x32_bf16 v[46:49], v[192:195], v[208:211], v[46:49]
	v_mfma_f32_16x16x32_bf16 v[38:41], v[196:199], v[208:211], v[38:41]
	ds_read_b128 v[208:211], v0 offset:4096
	s_waitcnt vmcnt(7)
	ds_write_b128 v228, v[6:9] offset:16384
	global_load_dwordx4 v[6:9], v236, s[50:51]
	s_waitcnt lgkmcnt(8)
	v_mfma_f32_16x16x32_bf16 v[34:37], v[166:169], v[238:241], v[34:37]
	v_mfma_f32_16x16x32_bf16 v[30:33], v[170:173], v[238:241], v[30:33]
	v_mfma_f32_16x16x32_bf16 v[26:29], v[192:195], v[238:241], v[26:29]
	v_mfma_f32_16x16x32_bf16 v[22:25], v[196:199], v[238:241], v[22:25]
	ds_read_b128 v[238:241], v0 offset:6144
	s_waitcnt vmcnt(7)
	ds_write_b128 v228, v[14:17] offset:24576
	global_load_dwordx4 v[14:17], v237, s[50:51]
	s_waitcnt lgkmcnt(7)
	v_mfma_f32_16x16x32_bf16 v[158:161], v[212:215], v[162:165], v[158:161]
	v_mfma_f32_16x16x32_bf16 v[154:157], v[216:219], v[162:165], v[154:157]
	v_mfma_f32_16x16x32_bf16 v[150:153], v[220:223], v[162:165], v[150:153]
	v_mfma_f32_16x16x32_bf16 v[146:149], v[224:227], v[162:165], v[146:149]
	ds_read_b128 v[162:165], v0 offset:8192
	s_waitcnt vmcnt(7)
	ds_write_b128 v229, v[18:21]
	global_load_dwordx4 v[18:21], v234, s[52:53]
	s_waitcnt lgkmcnt(7)
	v_mfma_f32_16x16x32_bf16 v[142:145], v[212:215], v[204:207], v[142:145]
	v_mfma_f32_16x16x32_bf16 v[138:141], v[216:219], v[204:207], v[138:141]
	v_mfma_f32_16x16x32_bf16 v[134:137], v[220:223], v[204:207], v[134:137]
	v_mfma_f32_16x16x32_bf16 v[130:133], v[224:227], v[204:207], v[130:133]
	ds_read_b128 v[204:207], v0 offset:10240
	s_waitcnt vmcnt(7)
	ds_write_b128 v229, v[42:45] offset:8192
	global_load_dwordx4 v[42:45], v235, s[52:53]
	s_waitcnt lgkmcnt(7)
	v_mfma_f32_16x16x32_bf16 v[126:129], v[212:215], v[208:211], v[126:129]
	v_mfma_f32_16x16x32_bf16 v[122:125], v[216:219], v[208:211], v[122:125]
	v_mfma_f32_16x16x32_bf16 v[118:121], v[220:223], v[208:211], v[118:121]
	v_mfma_f32_16x16x32_bf16 v[114:117], v[224:227], v[208:211], v[114:117]
	ds_read_b128 v[208:211], v0 offset:12288
	s_waitcnt vmcnt(7)
	ds_write_b128 v229, v[62:65] offset:16384
	global_load_dwordx4 v[62:65], v236, s[52:53]
	s_waitcnt lgkmcnt(7)
	v_mfma_f32_16x16x32_bf16 v[110:113], v[212:215], v[238:241], v[110:113]
	v_mfma_f32_16x16x32_bf16 v[106:109], v[216:219], v[238:241], v[106:109]
	v_mfma_f32_16x16x32_bf16 v[102:105], v[220:223], v[238:241], v[102:105]
	v_mfma_f32_16x16x32_bf16 v[98:101], v[224:227], v[238:241], v[98:101]
	ds_read_b128 v[238:241], v0 offset:14336
	s_waitcnt vmcnt(7)
	ds_write_b128 v229, v[74:77] offset:24576
	global_load_dwordx4 v[74:77], v237, s[52:53]
	s_waitcnt lgkmcnt(7)
	v_mfma_f32_16x16x32_bf16 v[94:97], v[212:215], v[162:165], v[94:97]
	v_mfma_f32_16x16x32_bf16 v[90:93], v[216:219], v[162:165], v[90:93]
	v_mfma_f32_16x16x32_bf16 v[86:89], v[220:223], v[162:165], v[86:89]
	v_mfma_f32_16x16x32_bf16 v[82:85], v[224:227], v[162:165], v[82:85]
	s_waitcnt lgkmcnt(0)
	s_setprio 0
	s_barrier
; template <int MI, int NJ> ...
;     ...
;   for (int kt = 0; kt < nk; ++kt) {
;     const int buf = kt & 1;
;     {
;       G8STORE(buf ^ 1);
;       const u16* ga_ = (kt + 2 < nk) ? Ag + (kt + 2) * 64 : Ag + nAoff;
;       const u16* gb_ = (kt + 2 < nk) ? Bg + (kt + 2) * 64 : Bg + nBoff;
;       G8LOADP(ga_, gb_);
;     }
;     __builtin_amdgcn_sched_barrier(0);
;     __builtin_amdgcn_s_setprio(1);
;     const u16* a = ra_ + buf * AROWS * 64;
;     const u16* b = rb_ + buf * BROWS * 64;
; #pragma unroll
;     for (int ks = 0; ks < 2; ++ks) {
;       const u16* a_ = ks ? a + dsw : a;
;       const u16* b_ = ks ? b + dsw : b;
;       bf16x8 bfr[NJ];
; #pragma unroll
;       for (int j = 0; j < NJ; ++j) bfr[j] = *(const bf16x8*)(b_ + j * 16 * 64);
; #pragma unroll
;       for (int ih = 0; ih < MI / 4; ++ih) {
;         bf16x8 af[4];
; #pragma unroll
;         for (int i = 0; i < 4; ++i) af[i] = *(const bf16x8*)(a_ + (ih * 4 + i) * 16 * 64);
; #pragma unroll
;         for (int i = 0; i < 4; ++i)
; #pragma unroll
;           for (int j = 0; j < NJ; ++j) acc[ih * 4 + i][j] = mfma16(af[i], bfr[j], acc[ih * 4 + i][j]);
;       }
;     }
;     __builtin_amdgcn_s_setprio(0);
;     __builtin_amdgcn_sched_barrier(0);
;     __syncthreads();
; __device__ __forceinline__ void phase_gemm_f32(const u16* A, const u16* Bt, int K, u16* out, u16* smem,
;                                                volatile LAS unsigned* vb_) {
;     ...
; #pragma unroll
;     for (int i = 0; i < 8; ++i)
; #pragma unroll
;       for (int j = 0; j < 4; ++j)
; #pragma unroll
;         for (int r = 0; r < 4; ++r)
;           smem[(wm * 128 + i * 16 + (lane >> 4) * 4 + r) * 264 + wn * 64 + j * 16 + (lane & 15)] = f2bf(acc[i][j][r]);
;     __syncthreads();
	s_add_i32 s44, s44, 1
	s_add_i32 s39, s39, 64
	s_addk_i32 s43, 0x4000
	s_and_b32 s45, s43, 0x4000
	s_xor_b32 s46, s45, 0x4000
	s_lshl_b32 s46, s46, 1
	v_add_u32_e32 v228, s46, v185
	v_add_u32_e32 v229, s46, v186
	s_add_i32 s46, s44, 2
	s_cmp_lt_u32 s46, s21
	s_cselect_b32 s47, 0, s12
	s_cselect_b32 s46, s39, s13
	s_cselect_b32 s49, 0, s37
	s_cselect_b32 s48, s39, s38
	s_lshl_b64 s[46:47], s[46:47], 1
	s_lshl_b64 s[48:49], s[48:49], 1
	s_add_u32 s50, s62, s46
	s_addc_u32 s51, s63, s47
	s_add_u32 s52, s64, s48
	s_addc_u32 s53, s65, s49
	s_lshl_b32 s45, s45, 1
	v_add_u32_e32 v0, s45, v187
	v_add_u32_e32 v191, s45, v188
	s_setprio 1
	ds_read_b128 v[166:169], v191
	ds_read_b128 v[162:165], v0
	ds_read_b128 v[170:173], v191 offset:2048
	ds_read_b128 v[192:195], v191 offset:4096
	ds_read_b128 v[196:199], v191 offset:6144
	v_mfma_f32_16x16x32_bf16 v[78:81], v[212:215], v[204:207], v[78:81]
	v_mfma_f32_16x16x32_bf16 v[70:73], v[216:219], v[204:207], v[70:73]
	v_mfma_f32_16x16x32_bf16 v[66:69], v[220:223], v[204:207], v[66:69]
	v_mfma_f32_16x16x32_bf16 v[58:61], v[224:227], v[204:207], v[58:61]
	ds_read_b128 v[204:207], v0 offset:2048
	v_mfma_f32_16x16x32_bf16 v[54:57], v[212:215], v[208:211], v[54:57]
	v_mfma_f32_16x16x32_bf16 v[50:53], v[216:219], v[208:211], v[50:53]
	v_mfma_f32_16x16x32_bf16 v[46:49], v[220:223], v[208:211], v[46:49]
	v_mfma_f32_16x16x32_bf16 v[38:41], v[224:227], v[208:211], v[38:41]
	ds_read_b128 v[208:211], v0 offset:4096
	v_mfma_f32_16x16x32_bf16 v[34:37], v[212:215], v[238:241], v[34:37]
	v_mfma_f32_16x16x32_bf16 v[30:33], v[216:219], v[238:241], v[30:33]
	v_mfma_f32_16x16x32_bf16 v[26:29], v[220:223], v[238:241], v[26:29]
	v_mfma_f32_16x16x32_bf16 v[22:25], v[224:227], v[238:241], v[22:25]
	ds_read_b128 v[238:241], v0 offset:6144
	v_add_u32_e32 v191, v191, v190
	s_setprio 0
	s_cmp_lg_u32 s21, s44
	s_cbranch_scc1 .LBB0_481
	v_and_b32_e32 v228, 15, v175
	v_bfe_u32 v229, v175, 8, 1
	v_lshl_or_b32 v228, v229, 7, v228
	v_mul_u32_u24_e32 v228, 0x210, v228
	v_bfe_u32 v229, v175, 6, 2
	v_lshl_add_u32 v228, v229, 7, v228
	v_bfe_u32 v229, v175, 4, 2
	v_lshl_add_u32 v228, v229, 3, v228
	v_cvt_pk_bf16_f32 v158, v158, v159
	v_cvt_pk_bf16_f32 v159, v160, v161
	v_cvt_pk_bf16_f32 v154, v154, v155
	v_cvt_pk_bf16_f32 v155, v156, v157
	v_cvt_pk_bf16_f32 v150, v150, v151
	v_cvt_pk_bf16_f32 v151, v152, v153
	v_cvt_pk_bf16_f32 v146, v146, v147
	v_cvt_pk_bf16_f32 v147, v148, v149
	ds_write_b64 v228, v[158:159]
	ds_write_b64 v228, v[154:155] offset:32
	ds_write_b64 v228, v[150:151] offset:64
	ds_write_b64 v228, v[146:147] offset:96
	v_cvt_pk_bf16_f32 v142, v142, v143
	v_cvt_pk_bf16_f32 v143, v144, v145
	v_cvt_pk_bf16_f32 v138, v138, v139
	v_cvt_pk_bf16_f32 v139, v140, v141
	v_cvt_pk_bf16_f32 v134, v134, v135
	v_cvt_pk_bf16_f32 v135, v136, v137
	v_cvt_pk_bf16_f32 v130, v130, v131
	v_cvt_pk_bf16_f32 v131, v132, v133
	ds_write_b64 v228, v[142:143] offset:8448
	ds_write_b64 v228, v[138:139] offset:8480
	ds_write_b64 v228, v[134:135] offset:8512
	ds_write_b64 v228, v[130:131] offset:8544
	v_cvt_pk_bf16_f32 v126, v126, v127
	v_cvt_pk_bf16_f32 v127, v128, v129
	v_cvt_pk_bf16_f32 v122, v122, v123
	v_cvt_pk_bf16_f32 v123, v124, v125
	v_cvt_pk_bf16_f32 v118, v118, v119
	v_cvt_pk_bf16_f32 v119, v120, v121
	v_cvt_pk_bf16_f32 v114, v114, v115
	v_cvt_pk_bf16_f32 v115, v116, v117
	ds_write_b64 v228, v[126:127] offset:16896
	ds_write_b64 v228, v[122:123] offset:16928
	ds_write_b64 v228, v[118:119] offset:16960
	ds_write_b64 v228, v[114:115] offset:16992
	v_cvt_pk_bf16_f32 v110, v110, v111
	v_cvt_pk_bf16_f32 v111, v112, v113
	v_cvt_pk_bf16_f32 v106, v106, v107
	v_cvt_pk_bf16_f32 v107, v108, v109
	v_cvt_pk_bf16_f32 v102, v102, v103
	v_cvt_pk_bf16_f32 v103, v104, v105
	v_cvt_pk_bf16_f32 v98, v98, v99
	v_cvt_pk_bf16_f32 v99, v100, v101
	ds_write_b64 v228, v[110:111] offset:25344
	ds_write_b64 v228, v[106:107] offset:25376
	ds_write_b64 v228, v[102:103] offset:25408
	ds_write_b64 v228, v[98:99] offset:25440
	v_cvt_pk_bf16_f32 v94, v94, v95
	v_cvt_pk_bf16_f32 v95, v96, v97
	v_cvt_pk_bf16_f32 v90, v90, v91
	v_cvt_pk_bf16_f32 v91, v92, v93
	v_cvt_pk_bf16_f32 v86, v86, v87
	v_cvt_pk_bf16_f32 v87, v88, v89
	v_cvt_pk_bf16_f32 v82, v82, v83
	v_cvt_pk_bf16_f32 v83, v84, v85
	ds_write_b64 v228, v[94:95] offset:33792
	ds_write_b64 v228, v[90:91] offset:33824
	ds_write_b64 v228, v[86:87] offset:33856
	ds_write_b64 v228, v[82:83] offset:33888
	v_cvt_pk_bf16_f32 v78, v78, v79
	v_cvt_pk_bf16_f32 v79, v80, v81
	v_cvt_pk_bf16_f32 v70, v70, v71
	v_cvt_pk_bf16_f32 v71, v72, v73
	v_cvt_pk_bf16_f32 v66, v66, v67
	v_cvt_pk_bf16_f32 v67, v68, v69
	v_cvt_pk_bf16_f32 v58, v58, v59
	v_cvt_pk_bf16_f32 v59, v60, v61
	ds_write_b64 v228, v[78:79] offset:42240
	ds_write_b64 v228, v[70:71] offset:42272
	ds_write_b64 v228, v[66:67] offset:42304
	ds_write_b64 v228, v[58:59] offset:42336
	v_cvt_pk_bf16_f32 v54, v54, v55
	v_cvt_pk_bf16_f32 v55, v56, v57
	v_cvt_pk_bf16_f32 v50, v50, v51
	v_cvt_pk_bf16_f32 v51, v52, v53
	v_cvt_pk_bf16_f32 v46, v46, v47
	v_cvt_pk_bf16_f32 v47, v48, v49
	v_cvt_pk_bf16_f32 v38, v38, v39
	v_cvt_pk_bf16_f32 v39, v40, v41
	ds_write_b64 v228, v[54:55] offset:50688
	ds_write_b64 v228, v[50:51] offset:50720
	ds_write_b64 v228, v[46:47] offset:50752
	ds_write_b64 v228, v[38:39] offset:50784
	v_cvt_pk_bf16_f32 v34, v34, v35
	v_cvt_pk_bf16_f32 v35, v36, v37
	v_cvt_pk_bf16_f32 v30, v30, v31
	v_cvt_pk_bf16_f32 v31, v32, v33
	v_cvt_pk_bf16_f32 v26, v26, v27
	v_cvt_pk_bf16_f32 v27, v28, v29
	v_cvt_pk_bf16_f32 v22, v22, v23
	v_cvt_pk_bf16_f32 v23, v24, v25
	ds_write_b64 v228, v[34:35] offset:59136
	ds_write_b64 v228, v[30:31] offset:59168
	ds_write_b64 v228, v[26:27] offset:59200
	ds_write_b64 v228, v[22:23] offset:59232
	s_ashr_i32 s43, s42, 31
	v_mov_b32_e32 v34, v175
	s_lshl_b64 s[12:13], s[42:43], 1
	s_waitcnt lgkmcnt(0)
	s_barrier
; #define RTID opaque_tid()
; __device__ __forceinline__ void phase_gemm_f32(const u16* A, const u16* Bt, int K, u16* out, u16* smem,
;                                                volatile LAS unsigned* vb_) {
;     ...
;     const int tid2 = RTID;
; #pragma unroll
;     for (int k = 0; k < 16; ++k) {
;       const int c = tid2 + 512 * k;
;       const int row = c >> 5, ch = c & 31;
;       const uint4 v = *(const uint4*)(smem + row * 264 + ch * 8);
;       *(uint4*)(out + (size_t)(mt * 256 + row) * 1024 + nt * 256 + ch * 8) = v;
;     }
;     __syncthreads();
	s_add_u32 s12, s11, s12
	s_addc_u32 s13, s20, s13
	v_lshlrev_b32_e32 v0, 4, v34
	v_and_b32_e32 v0, 0x1f0, v0
	v_ashrrev_i32_e32 v26, 5, v34
	v_mad_u32_u24 v22, v26, s2, v0
	v_add_u32_e32 v23, 0x10800, v22
	ds_read_b128 v[98:101], v22
	ds_read_b128 v[102:105], v22 offset:8448
	ds_read_b128 v[106:109], v22 offset:16896
	ds_read_b128 v[110:113], v22 offset:25344
	ds_read_b128 v[114:117], v22 offset:33792
	ds_read_b128 v[118:121], v22 offset:42240
	ds_read_b128 v[122:125], v22 offset:50688
	ds_read_b128 v[126:129], v22 offset:59136
	v_add_u32_e32 v26, s23, v26
	v_ashrrev_i32_e32 v27, 31, v26
	v_lshlrev_b64 v[26:27], 11, v[26:27]
	v_lshl_add_u64 v[32:33], s[12:13], 0, v[26:27]
	v_lshl_add_u64 v[32:33], v[32:33], 0, v[0:1]
	s_mov_b32 s48, 0x8000
	s_mov_b32 s49, 0
	s_and_b64 vcc, exec, s[40:41]
	s_mov_b32 s37, s36
	s_waitcnt lgkmcnt(7)
	global_store_dwordx4 v[32:33], v[98:101], off
	s_nop 0
	ds_read_b128 v[98:101], v23
	v_lshl_add_u64 v[32:33], v[32:33], 0, s[48:49]
	s_waitcnt lgkmcnt(7)
	global_store_dwordx4 v[32:33], v[102:105], off
	s_nop 0
	ds_read_b128 v[102:105], v23 offset:8448
	v_lshl_add_u64 v[32:33], v[32:33], 0, s[48:49]
	s_waitcnt lgkmcnt(7)
	global_store_dwordx4 v[32:33], v[106:109], off
	s_nop 0
	ds_read_b128 v[106:109], v23 offset:16896
	v_lshl_add_u64 v[32:33], v[32:33], 0, s[48:49]
	s_waitcnt lgkmcnt(7)
	global_store_dwordx4 v[32:33], v[110:113], off
	s_nop 0
	ds_read_b128 v[110:113], v23 offset:25344
	v_lshl_add_u64 v[32:33], v[32:33], 0, s[48:49]
	s_waitcnt lgkmcnt(7)
	global_store_dwordx4 v[32:33], v[114:117], off
	s_nop 0
	ds_read_b128 v[114:117], v23 offset:33792
	v_lshl_add_u64 v[32:33], v[32:33], 0, s[48:49]
	s_waitcnt lgkmcnt(7)
	global_store_dwordx4 v[32:33], v[118:121], off
	s_nop 0
	ds_read_b128 v[118:121], v23 offset:42240
	v_lshl_add_u64 v[32:33], v[32:33], 0, s[48:49]
	s_waitcnt lgkmcnt(7)
	global_store_dwordx4 v[32:33], v[122:125], off
	s_nop 0
	ds_read_b128 v[122:125], v23 offset:50688
	v_lshl_add_u64 v[32:33], v[32:33], 0, s[48:49]
	s_waitcnt lgkmcnt(7)
	global_store_dwordx4 v[32:33], v[126:129], off
	s_nop 0
	ds_read_b128 v[126:129], v23 offset:59136
	v_lshl_add_u64 v[32:33], v[32:33], 0, s[48:49]
	s_waitcnt lgkmcnt(7)
	global_store_dwordx4 v[32:33], v[98:101], off
	v_lshl_add_u64 v[32:33], v[32:33], 0, s[48:49]
	s_waitcnt lgkmcnt(6)
	global_store_dwordx4 v[32:33], v[102:105], off
	v_lshl_add_u64 v[32:33], v[32:33], 0, s[48:49]
	s_waitcnt lgkmcnt(5)
	global_store_dwordx4 v[32:33], v[106:109], off
	v_lshl_add_u64 v[32:33], v[32:33], 0, s[48:49]
	s_waitcnt lgkmcnt(4)
	global_store_dwordx4 v[32:33], v[110:113], off
	v_lshl_add_u64 v[32:33], v[32:33], 0, s[48:49]
	s_waitcnt lgkmcnt(3)
	global_store_dwordx4 v[32:33], v[114:117], off
	v_lshl_add_u64 v[32:33], v[32:33], 0, s[48:49]
	s_waitcnt lgkmcnt(2)
	global_store_dwordx4 v[32:33], v[118:121], off
	v_lshl_add_u64 v[32:33], v[32:33], 0, s[48:49]
	s_waitcnt lgkmcnt(1)
	global_store_dwordx4 v[32:33], v[122:125], off
	v_lshl_add_u64 v[32:33], v[32:33], 0, s[48:49]
	s_waitcnt lgkmcnt(0)
	global_store_dwordx4 v[32:33], v[126:129], off
	s_mov_b64 s[12:13], -1
	s_barrier
	s_cbranch_vccz .LBB0_478
